# pooling item: 16 window-sum loops unrolled by 8 (eight LDS reads in flight, same add order); chunk-MLP item second staging loop and epilogue loads de-serialized
# speedup vs baseline: 1.0428x; 1.0103x over previous
.LBB0_605:
	s_or_b64 exec, exec, s[0:1]
	s_waitcnt lgkmcnt(0)
	s_barrier
	ds_read_b32 v1, v131 offset:228
	s_movk_i32 s0, 0x2ff
	s_waitcnt lgkmcnt(0)
	s_barrier
	v_cmp_lt_i32_e32 vcc, s0, v1
	v_readfirstlane_b32 s20, v1
	s_mov_b64 s[0:1], -1
	s_cbranch_vccnz .LBB0_600
	s_cmpk_gt_i32 s20, 0xff
	s_cbranch_scc0 .LBB0_702
	s_cmpk_gt_u32 s20, 0x1ff
	s_cbranch_scc0 .LBB0_612
	v_mov_b32_e32 v1, v0
	ds_read_b64 v[2:3], v131 offset:88
	s_and_b32 s0, s20, 3
	v_readlane_b32 s4, v254, 63
	s_or_b32 s10, s0, s4
	s_lshl_b32 s96, s10, 14
	s_lshl_b32 s1, s20, 5
	s_waitcnt lgkmcnt(0)
	v_readfirstlane_b32 s7, v2
	s_lshl_b64 s[4:5], s[96:97], 2
	v_lshlrev_b32_e32 v2, 2, v1
	v_readfirstlane_b32 s6, v3
	s_add_u32 s4, s7, s4
	v_and_b32_e32 v2, 0x7c, v2
	v_ashrrev_i32_e32 v3, 5, v1
	s_addc_u32 s5, s6, s5
	v_lshlrev_b32_e32 v130, 2, v2
	s_waitcnt vmcnt(9)
	v_lshlrev_b32_e32 v6, 7, v3
	v_lshl_add_u64 v[4:5], s[4:5], 0, v[130:131]
	v_ashrrev_i32_e32 v7, 31, v6
	v_lshl_add_u64 v[6:7], v[6:7], 2, v[4:5]
	s_barrier
	v_lshl_add_u32 v2, v2, 1, v212
	v_lshl_add_u32 v30, v3, 9, v130
	v_mul_u32_u24_e32 v31, 0x110, v3
	v_add_u32_e32 v31, v31, v2
	global_load_dwordx4 v[6:9], v30, s[4:5]
	s_add_u32 s4, s4, 0x2000
	s_addc_u32 s5, s5, 0
	global_load_dwordx4 v[10:13], v30, s[4:5]
	s_add_u32 s4, s4, 0x2000
	s_addc_u32 s5, s5, 0
	global_load_dwordx4 v[14:17], v30, s[4:5]
	s_add_u32 s4, s4, 0x2000
	s_addc_u32 s5, s5, 0
	global_load_dwordx4 v[18:21], v30, s[4:5]
	s_add_u32 s4, s4, 0x2000
	s_addc_u32 s5, s5, 0
	global_load_dwordx4 v[22:25], v30, s[4:5]
	s_add_u32 s4, s4, 0x2000
	s_addc_u32 s5, s5, 0
	global_load_dwordx4 v[26:29], v30, s[4:5]
	s_add_u32 s4, s4, 0x2000
	s_addc_u32 s5, s5, 0
	global_load_dwordx4 v[32:35], v30, s[4:5]
	s_add_u32 s4, s4, 0x2000
	s_addc_u32 s5, s5, 0
	global_load_dwordx4 v[36:39], v30, s[4:5]
	s_movk_i32 s6, 0x110
	s_waitcnt vmcnt(7)
	v_cvt_pk_bf16_f32 v6, v6, v7
	v_cvt_pk_bf16_f32 v7, v8, v9
	ds_write_b64 v31, v[6:7]
	s_waitcnt vmcnt(6)
	v_cvt_pk_bf16_f32 v10, v10, v11
	v_cvt_pk_bf16_f32 v11, v12, v13
	ds_write_b64 v31, v[10:11] offset:4352
	s_waitcnt vmcnt(5)
	v_cvt_pk_bf16_f32 v14, v14, v15
	v_cvt_pk_bf16_f32 v15, v16, v17
	ds_write_b64 v31, v[14:15] offset:8704
	s_waitcnt vmcnt(4)
	v_cvt_pk_bf16_f32 v18, v18, v19
	v_cvt_pk_bf16_f32 v19, v20, v21
	ds_write_b64 v31, v[18:19] offset:13056
	s_waitcnt vmcnt(3)
	v_cvt_pk_bf16_f32 v22, v22, v23
	v_cvt_pk_bf16_f32 v23, v24, v25
	ds_write_b64 v31, v[22:23] offset:17408
	s_waitcnt vmcnt(2)
	v_cvt_pk_bf16_f32 v26, v26, v27
	v_cvt_pk_bf16_f32 v27, v28, v29
	ds_write_b64 v31, v[26:27] offset:21760
	s_waitcnt vmcnt(1)
	v_cvt_pk_bf16_f32 v32, v32, v33
	v_cvt_pk_bf16_f32 v33, v34, v35
	ds_write_b64 v31, v[32:33] offset:26112
	s_waitcnt vmcnt(0)
	v_cvt_pk_bf16_f32 v36, v36, v37
	v_cvt_pk_bf16_f32 v37, v38, v39
	ds_write_b64 v31, v[36:37] offset:30464
	s_lshl_b32 s11, s0, 6
	s_and_b32 s12, s1, 0x1f80
	s_movk_i32 s13, 0x5ff
	s_mul_i32 s4, s12, 0x2200
	s_add_u32 s4, s28, s4
	s_addc_u32 s5, s29, 0
	s_lshl_b32 s6, s11, 2
	s_add_u32 s4, s4, s6
	s_addc_u32 s5, s5, 0
	v_lshrrev_b32_e32 v8, 4, v0
	v_lshlrev_b32_e32 v9, 2, v0
	v_and_b32_e32 v9, 60, v9
	v_mul_u32_u24_e32 v22, 0x2200, v8
	v_lshl_add_u32 v22, v9, 2, v22
	global_load_dwordx4 v[4:7], v22, s[4:5] offset:1024
	s_add_u32 s4, s4, 0x44000
	s_addc_u32 s5, s5, 0
	global_load_dwordx4 v[10:13], v22, s[4:5] offset:1024
	s_add_u32 s4, s4, 0x44000
	s_addc_u32 s5, s5, 0
	global_load_dwordx4 v[14:17], v22, s[4:5] offset:1024
	s_add_u32 s4, s4, 0x44000
	s_addc_u32 s5, s5, 0
	global_load_dwordx4 v[18:21], v22, s[4:5] offset:1024
	v_mul_u32_u24_e32 v23, 0x110, v9
	v_lshl_add_u32 v23, v8, 1, v23
	v_add_u32_e32 v23, s73, v23
	s_waitcnt vmcnt(3)
	v_cvt_pk_bf16_f32 v24, v4, v131
	ds_write_b16 v23, v24 offset:34816
	v_cvt_pk_bf16_f32 v24, v5, v131
	ds_write_b16 v23, v24 offset:35088
	v_cvt_pk_bf16_f32 v24, v6, v131
	ds_write_b16 v23, v24 offset:35360
	v_cvt_pk_bf16_f32 v24, v7, v131
	ds_write_b16 v23, v24 offset:35632
	s_waitcnt vmcnt(2)
	v_cvt_pk_bf16_f32 v24, v10, v131
	ds_write_b16 v23, v24 offset:34880
	v_cvt_pk_bf16_f32 v24, v11, v131
	ds_write_b16 v23, v24 offset:35152
	v_cvt_pk_bf16_f32 v24, v12, v131
	ds_write_b16 v23, v24 offset:35424
	v_cvt_pk_bf16_f32 v24, v13, v131
	ds_write_b16 v23, v24 offset:35696
	s_waitcnt vmcnt(1)
	v_cvt_pk_bf16_f32 v24, v14, v131
	ds_write_b16 v23, v24 offset:34944
	v_cvt_pk_bf16_f32 v24, v15, v131
	ds_write_b16 v23, v24 offset:35216
	v_cvt_pk_bf16_f32 v24, v16, v131
	ds_write_b16 v23, v24 offset:35488
	v_cvt_pk_bf16_f32 v24, v17, v131
	ds_write_b16 v23, v24 offset:35760
	s_waitcnt vmcnt(0)
	v_cvt_pk_bf16_f32 v24, v18, v131
	ds_write_b16 v23, v24 offset:35008
	v_cvt_pk_bf16_f32 v24, v19, v131
	ds_write_b16 v23, v24 offset:35280
	v_cvt_pk_bf16_f32 v24, v20, v131
	ds_write_b16 v23, v24 offset:35552
	v_cvt_pk_bf16_f32 v24, v21, v131
	ds_write_b16 v23, v24 offset:35824
	v_bfe_u32 v28, v1, 4, 2
	v_ashrrev_i32_e32 v2, 2, v1
	v_and_b32_e32 v7, 15, v1
	v_bfi_b32 v1, -16, v2, v1
	v_lshl_add_u32 v6, v28, 4, v212
	s_movk_i32 s4, 0x110
	v_mad_u64_u32 v[26:27], s[0:1], v1, s4, v[6:7]
	v_mad_u32_u24 v27, v7, s4, v6
	s_waitcnt lgkmcnt(0)
	s_barrier
	ds_read_b128 v[2:5], v26
	ds_read_b128 v[6:9], v27 offset:34816
	ds_read_b128 v[10:13], v27 offset:39168
	ds_read_b128 v[14:17], v27 offset:43520
	ds_read_b128 v[18:21], v27 offset:47872
	s_waitcnt lgkmcnt(3)
	v_mfma_f32_16x16x32_bf16 v[6:9], v[6:9], v[2:5], 0
	v_lshl_or_b32 v30, v28, 2, s11
	v_lshlrev_b32_e32 v130, 2, v30
	v_readlane_b32 s79, v254, 50
	s_waitcnt lgkmcnt(2)
	v_mfma_f32_16x16x32_bf16 v[10:13], v[10:13], v[2:5], 0
	s_waitcnt lgkmcnt(1)
	v_mfma_f32_16x16x32_bf16 v[14:17], v[14:17], v[2:5], 0
	s_waitcnt lgkmcnt(0)
	v_mfma_f32_16x16x32_bf16 v[2:5], v[18:21], v[2:5], 0
	ds_read_b128 v[18:21], v26 offset:64
	ds_read_b128 v[22:25], v27 offset:34880
	s_waitcnt lgkmcnt(0)
	v_mfma_f32_16x16x32_bf16 v[6:9], v[22:25], v[18:21], v[6:9]
	ds_read_b128 v[22:25], v27 offset:39232
	s_waitcnt lgkmcnt(0)
	v_mfma_f32_16x16x32_bf16 v[10:13], v[22:25], v[18:21], v[10:13]
	ds_read_b128 v[22:25], v27 offset:43584
	s_waitcnt lgkmcnt(0)
	v_mfma_f32_16x16x32_bf16 v[14:17], v[22:25], v[18:21], v[14:17]
	ds_read_b128 v[22:25], v27 offset:47936
	s_waitcnt lgkmcnt(0)
	v_mfma_f32_16x16x32_bf16 v[2:5], v[22:25], v[18:21], v[2:5]
	ds_read_b128 v[18:21], v26 offset:128
	ds_read_b128 v[22:25], v27 offset:34944
	s_waitcnt lgkmcnt(0)
	v_mfma_f32_16x16x32_bf16 v[6:9], v[22:25], v[18:21], v[6:9]
	ds_read_b128 v[22:25], v27 offset:39296
	s_waitcnt lgkmcnt(0)
	v_mfma_f32_16x16x32_bf16 v[10:13], v[22:25], v[18:21], v[10:13]
	ds_read_b128 v[22:25], v27 offset:43648
	s_waitcnt lgkmcnt(0)
	v_mfma_f32_16x16x32_bf16 v[14:17], v[22:25], v[18:21], v[14:17]
	ds_read_b128 v[22:25], v27 offset:48000
	s_waitcnt lgkmcnt(0)
	v_mfma_f32_16x16x32_bf16 v[2:5], v[22:25], v[18:21], v[2:5]
	ds_read_b128 v[18:21], v26 offset:192
	ds_read_b128 v[22:25], v27 offset:35008
	s_waitcnt lgkmcnt(0)
	v_mfma_f32_16x16x32_bf16 v[22:25], v[22:25], v[18:21], v[6:9]
	s_nop 2
	ds_read_b128 v[6:9], v27 offset:39360
	s_waitcnt lgkmcnt(0)
	v_mfma_f32_16x16x32_bf16 v[10:13], v[6:9], v[18:21], v[10:13]
	ds_read_b128 v[6:9], v27 offset:43712
	s_waitcnt lgkmcnt(0)
	v_mfma_f32_16x16x32_bf16 v[6:9], v[6:9], v[18:21], v[14:17]
	s_nop 2
	ds_read_b128 v[14:17], v27 offset:48064
	s_waitcnt lgkmcnt(0)
	v_mfma_f32_16x16x32_bf16 v[2:5], v[14:17], v[18:21], v[2:5]
	ds_read_b64 v[16:17], v131 offset:96
	v_lshl_add_u32 v18, s10, 7, v1
	v_ashrrev_i32_e32 v19, 31, v18
	v_add_u32_e32 v14, s12, v1
	v_ashrrev_i32_e32 v15, 31, v14
	s_waitcnt lgkmcnt(0)
	v_readfirstlane_b32 s0, v17
	v_readfirstlane_b32 s1, v16
	s_nop 0
	v_mov_b32_e32 v17, s0
	v_mov_b32_e32 v16, s1
	v_lshl_add_u64 v[16:17], v[18:19], 2, v[16:17]
	flat_load_dword v1, v[16:17]
	v_mov_b64_e32 v[16:17], s[28:29]
	v_mad_i64_i32 v[16:17], s[0:1], v14, s36, v[16:17]
	v_lshlrev_b64 v[14:15], 11, v[14:15]
	v_readlane_b32 s0, v253, 55
	v_lshl_add_u64 v[26:27], s[30:31], 0, v[14:15]
	v_readlane_b32 s1, v253, 56
	v_lshl_add_u64 v[16:17], v[16:17], 0, v[130:131]
	v_lshlrev_b32_e32 v130, 1, v30
	v_lshl_add_u64 v[28:29], s[0:1], 0, v[14:15]
	v_lshl_add_u64 v[14:15], v[26:27], 0, v[130:131]
	global_load_dwordx4 v[32:35], v[16:17], off
	global_load_dwordx4 v[36:39], v[16:17], off offset:64
	global_load_dwordx4 v[40:43], v[16:17], off offset:128
	global_load_dwordx4 v[44:47], v[16:17], off offset:192
	global_load_dwordx2 v[48:49], v[14:15], off
	global_load_dwordx2 v[50:51], v[14:15], off offset:32
	global_load_dwordx2 v[52:53], v[14:15], off offset:64
	global_load_dwordx2 v[54:55], v[14:15], off offset:96
	s_mov_b64 s[0:1], 0
	v_lshl_add_u64 v[18:19], v[28:29], 0, v[130:131]
	s_waitcnt vmcnt(0) lgkmcnt(0)
	v_add_f32_e32 v22, v22, v1
	v_mul_f32_e32 v22, v22, v32
	v_lshlrev_b32_e32 v56, 16, v48
	v_mul_f32_e32 v22, v22, v56
	v_add_f32_e32 v23, v23, v1
	v_mul_f32_e32 v23, v23, v33
	v_and_b32_e32 v56, 0xffff0000, v48
	v_mul_f32_e32 v23, v23, v56
	v_add_f32_e32 v24, v24, v1
	v_mul_f32_e32 v24, v24, v34
	v_lshlrev_b32_e32 v56, 16, v49
	v_mul_f32_e32 v24, v24, v56
	v_add_f32_e32 v25, v25, v1
	v_mul_f32_e32 v25, v25, v35
	v_and_b32_e32 v56, 0xffff0000, v49
	v_mul_f32_e32 v25, v25, v56
	v_cvt_pk_bf16_f32 v22, v22, v23
	v_cvt_pk_bf16_f32 v23, v24, v25
	global_store_dwordx2 v[18:19], v[22:23], off
	v_add_f32_e32 v10, v10, v1
	v_mul_f32_e32 v10, v10, v36
	v_lshlrev_b32_e32 v56, 16, v50
	v_mul_f32_e32 v10, v10, v56
	v_add_f32_e32 v11, v11, v1
	v_mul_f32_e32 v11, v11, v37
	v_and_b32_e32 v56, 0xffff0000, v50
	v_mul_f32_e32 v11, v11, v56
	v_add_f32_e32 v12, v12, v1
	v_mul_f32_e32 v12, v12, v38
	v_lshlrev_b32_e32 v56, 16, v51
	v_mul_f32_e32 v12, v12, v56
	v_add_f32_e32 v13, v13, v1
	v_mul_f32_e32 v13, v13, v39
	v_and_b32_e32 v56, 0xffff0000, v51
	v_mul_f32_e32 v13, v13, v56
	v_cvt_pk_bf16_f32 v10, v10, v11
	v_cvt_pk_bf16_f32 v11, v12, v13
	global_store_dwordx2 v[18:19], v[10:11], off offset:32
	v_add_f32_e32 v6, v6, v1
	v_mul_f32_e32 v6, v6, v40
	v_lshlrev_b32_e32 v56, 16, v52
	v_mul_f32_e32 v6, v6, v56
	v_add_f32_e32 v7, v7, v1
	v_mul_f32_e32 v7, v7, v41
	v_and_b32_e32 v56, 0xffff0000, v52
	v_mul_f32_e32 v7, v7, v56
	v_add_f32_e32 v8, v8, v1
	v_mul_f32_e32 v8, v8, v42
	v_lshlrev_b32_e32 v56, 16, v53
	v_mul_f32_e32 v8, v8, v56
	v_add_f32_e32 v9, v9, v1
	v_mul_f32_e32 v9, v9, v43
	v_and_b32_e32 v56, 0xffff0000, v53
	v_mul_f32_e32 v9, v9, v56
	v_cvt_pk_bf16_f32 v6, v6, v7
	v_cvt_pk_bf16_f32 v7, v8, v9
	global_store_dwordx2 v[18:19], v[6:7], off offset:64
	v_add_f32_e32 v2, v2, v1
	v_mul_f32_e32 v2, v2, v44
	v_lshlrev_b32_e32 v56, 16, v54
	v_mul_f32_e32 v2, v2, v56
	v_add_f32_e32 v3, v3, v1
	v_mul_f32_e32 v3, v3, v45
	v_and_b32_e32 v56, 0xffff0000, v54
	v_mul_f32_e32 v3, v3, v56
	v_add_f32_e32 v4, v4, v1
	v_mul_f32_e32 v4, v4, v46
	v_lshlrev_b32_e32 v56, 16, v55
	v_mul_f32_e32 v4, v4, v56
	v_add_f32_e32 v5, v5, v1
	v_mul_f32_e32 v5, v5, v47
	v_and_b32_e32 v56, 0xffff0000, v55
	v_mul_f32_e32 v5, v5, v56
	v_cvt_pk_bf16_f32 v2, v2, v3
	v_cvt_pk_bf16_f32 v3, v4, v5
	global_store_dwordx2 v[18:19], v[2:3], off offset:96

.LBB0_639:
	ds_read_b32 v13, v11
	ds_read_b32 v57, v11 offset:1024
	ds_read_b32 v58, v11 offset:2048
	ds_read_b32 v59, v11 offset:3072
	ds_read_b32 v60, v11 offset:4096
	ds_read_b32 v61, v11 offset:5120
	ds_read_b32 v62, v11 offset:6144
	ds_read_b32 v63, v11 offset:7168
	v_add_u32_e32 v65, 1, v12
	v_add_u32_e32 v64, 2, v12
	s_waitcnt lgkmcnt(0)
	v_add_f32_e32 v8, v8, v13
	v_cmp_lt_i32_e32 vcc, v65, v10
	v_add_u32_e32 v65, 3, v12
	s_nop 0
	v_cndmask_b32_e32 v57, 0, v57, vcc
	v_add_f32_e32 v8, v8, v57
	v_cmp_lt_i32_e32 vcc, v64, v10
	v_add_u32_e32 v64, 4, v12
	s_nop 0
	v_cndmask_b32_e32 v58, 0, v58, vcc
	v_add_f32_e32 v8, v8, v58
	v_cmp_lt_i32_e32 vcc, v65, v10
	v_add_u32_e32 v65, 5, v12
	s_nop 0
	v_cndmask_b32_e32 v59, 0, v59, vcc
	v_add_f32_e32 v8, v8, v59
	v_cmp_lt_i32_e32 vcc, v64, v10
	v_add_u32_e32 v64, 6, v12
	s_nop 0
	v_cndmask_b32_e32 v60, 0, v60, vcc
	v_add_f32_e32 v8, v8, v60
	v_cmp_lt_i32_e32 vcc, v65, v10
	v_add_u32_e32 v65, 7, v12
	s_nop 0
	v_cndmask_b32_e32 v61, 0, v61, vcc
	v_add_f32_e32 v8, v8, v61
	v_cmp_lt_i32_e32 vcc, v64, v10
	s_nop 0
	s_nop 0
	v_cndmask_b32_e32 v62, 0, v62, vcc
	v_add_f32_e32 v8, v8, v62
	v_cmp_lt_i32_e32 vcc, v65, v10
	s_nop 0
	s_nop 0
	v_cndmask_b32_e32 v63, 0, v63, vcc
	v_add_f32_e32 v8, v8, v63
	v_add_u32_e32 v12, 8, v12
	v_cmp_ge_i32_e32 vcc, v12, v10
	v_add_u32_e32 v11, 0x2000, v11
	s_or_b64 s[4:5], vcc, s[4:5]
	s_andn2_b64 exec, exec, s[4:5]
	s_cbranch_execnz .LBB0_639
	s_or_b64 exec, exec, s[4:5]

.LBB0_643:
	ds_read_b32 v15, v13
	ds_read_b32 v57, v13 offset:1024
	ds_read_b32 v58, v13 offset:2048
	ds_read_b32 v59, v13 offset:3072
	ds_read_b32 v60, v13 offset:4096
	ds_read_b32 v61, v13 offset:5120
	ds_read_b32 v62, v13 offset:6144
	ds_read_b32 v63, v13 offset:7168
	v_add_u32_e32 v65, 1, v14
	v_add_u32_e32 v64, 2, v14
	s_waitcnt lgkmcnt(0)
	v_add_f32_e32 v9, v9, v15
	v_cmp_lt_i32_e32 vcc, v65, v12
	v_add_u32_e32 v65, 3, v14
	s_nop 0
	v_cndmask_b32_e32 v57, 0, v57, vcc
	v_add_f32_e32 v9, v9, v57
	v_cmp_lt_i32_e32 vcc, v64, v12
	v_add_u32_e32 v64, 4, v14
	s_nop 0
	v_cndmask_b32_e32 v58, 0, v58, vcc
	v_add_f32_e32 v9, v9, v58
	v_cmp_lt_i32_e32 vcc, v65, v12
	v_add_u32_e32 v65, 5, v14
	s_nop 0
	v_cndmask_b32_e32 v59, 0, v59, vcc
	v_add_f32_e32 v9, v9, v59
	v_cmp_lt_i32_e32 vcc, v64, v12
	v_add_u32_e32 v64, 6, v14
	s_nop 0
	v_cndmask_b32_e32 v60, 0, v60, vcc
	v_add_f32_e32 v9, v9, v60
	v_cmp_lt_i32_e32 vcc, v65, v12
	v_add_u32_e32 v65, 7, v14
	s_nop 0
	v_cndmask_b32_e32 v61, 0, v61, vcc
	v_add_f32_e32 v9, v9, v61
	v_cmp_lt_i32_e32 vcc, v64, v12
	s_nop 0
	s_nop 0
	v_cndmask_b32_e32 v62, 0, v62, vcc
	v_add_f32_e32 v9, v9, v62
	v_cmp_lt_i32_e32 vcc, v65, v12
	s_nop 0
	s_nop 0
	v_cndmask_b32_e32 v63, 0, v63, vcc
	v_add_f32_e32 v9, v9, v63
	v_add_u32_e32 v14, 8, v14
	v_cmp_ge_i32_e32 vcc, v14, v12
	v_add_u32_e32 v13, 0x2000, v13
	s_or_b64 s[4:5], vcc, s[4:5]
	s_andn2_b64 exec, exec, s[4:5]
	s_cbranch_execnz .LBB0_643
	s_or_b64 exec, exec, s[4:5]

.LBB0_695:
	ds_read_b32 v14, v12
	ds_read_b32 v57, v12 offset:1024
	ds_read_b32 v58, v12 offset:2048
	ds_read_b32 v59, v12 offset:3072
	ds_read_b32 v60, v12 offset:4096
	ds_read_b32 v61, v12 offset:5120
	ds_read_b32 v62, v12 offset:6144
	ds_read_b32 v63, v12 offset:7168
	v_add_u32_e32 v65, 1, v13
	v_add_u32_e32 v64, 2, v13
	s_waitcnt lgkmcnt(0)
	v_add_f32_e32 v7, v7, v14
	v_cmp_lt_i32_e32 vcc, v65, v11
	v_add_u32_e32 v65, 3, v13
	s_nop 0
	v_cndmask_b32_e32 v57, 0, v57, vcc
	v_add_f32_e32 v7, v7, v57
	v_cmp_lt_i32_e32 vcc, v64, v11
	v_add_u32_e32 v64, 4, v13
	s_nop 0
	v_cndmask_b32_e32 v58, 0, v58, vcc
	v_add_f32_e32 v7, v7, v58
	v_cmp_lt_i32_e32 vcc, v65, v11
	v_add_u32_e32 v65, 5, v13
	s_nop 0
	v_cndmask_b32_e32 v59, 0, v59, vcc
	v_add_f32_e32 v7, v7, v59
	v_cmp_lt_i32_e32 vcc, v64, v11
	v_add_u32_e32 v64, 6, v13
	s_nop 0
	v_cndmask_b32_e32 v60, 0, v60, vcc
	v_add_f32_e32 v7, v7, v60
	v_cmp_lt_i32_e32 vcc, v65, v11
	v_add_u32_e32 v65, 7, v13
	s_nop 0
	v_cndmask_b32_e32 v61, 0, v61, vcc
	v_add_f32_e32 v7, v7, v61
	v_cmp_lt_i32_e32 vcc, v64, v11
	s_nop 0
	s_nop 0
	v_cndmask_b32_e32 v62, 0, v62, vcc
	v_add_f32_e32 v7, v7, v62
	v_cmp_lt_i32_e32 vcc, v65, v11
	s_nop 0
	s_nop 0
	v_cndmask_b32_e32 v63, 0, v63, vcc
	v_add_f32_e32 v7, v7, v63
	v_add_u32_e32 v13, 8, v13
	v_cmp_ge_i32_e32 vcc, v13, v11
	v_add_u32_e32 v12, 0x2000, v12
	s_or_b64 s[4:5], vcc, s[4:5]
	s_andn2_b64 exec, exec, s[4:5]
	s_cbranch_execnz .LBB0_695
	s_or_b64 exec, exec, s[4:5]

.LBB0_699:
	ds_read_b32 v10, v8
	ds_read_b32 v57, v8 offset:1024
	ds_read_b32 v58, v8 offset:2048
	ds_read_b32 v59, v8 offset:3072
	ds_read_b32 v60, v8 offset:4096
	ds_read_b32 v61, v8 offset:5120
	ds_read_b32 v62, v8 offset:6144
	ds_read_b32 v63, v8 offset:7168
	v_add_u32_e32 v65, 1, v9
	v_add_u32_e32 v64, 2, v9
	s_waitcnt lgkmcnt(0)
	v_add_f32_e32 v4, v4, v10
	v_cmp_lt_i32_e32 vcc, v65, v7
	v_add_u32_e32 v65, 3, v9
	s_nop 0
	v_cndmask_b32_e32 v57, 0, v57, vcc
	v_add_f32_e32 v4, v4, v57
	v_cmp_lt_i32_e32 vcc, v64, v7
	v_add_u32_e32 v64, 4, v9
	s_nop 0
	v_cndmask_b32_e32 v58, 0, v58, vcc
	v_add_f32_e32 v4, v4, v58
	v_cmp_lt_i32_e32 vcc, v65, v7
	v_add_u32_e32 v65, 5, v9
	s_nop 0
	v_cndmask_b32_e32 v59, 0, v59, vcc
	v_add_f32_e32 v4, v4, v59
	v_cmp_lt_i32_e32 vcc, v64, v7
	v_add_u32_e32 v64, 6, v9
	s_nop 0
	v_cndmask_b32_e32 v60, 0, v60, vcc
	v_add_f32_e32 v4, v4, v60
	v_cmp_lt_i32_e32 vcc, v65, v7
	v_add_u32_e32 v65, 7, v9
	s_nop 0
	v_cndmask_b32_e32 v61, 0, v61, vcc
	v_add_f32_e32 v4, v4, v61
	v_cmp_lt_i32_e32 vcc, v64, v7
	s_nop 0
	s_nop 0
	v_cndmask_b32_e32 v62, 0, v62, vcc
	v_add_f32_e32 v4, v4, v62
	v_cmp_lt_i32_e32 vcc, v65, v7
	s_nop 0
	s_nop 0
	v_cndmask_b32_e32 v63, 0, v63, vcc
	v_add_f32_e32 v4, v4, v63
	v_add_u32_e32 v9, 8, v9
	v_cmp_ge_i32_e32 vcc, v9, v7
	v_add_u32_e32 v8, 0x2000, v8
	s_or_b64 s[4:5], vcc, s[4:5]
	s_andn2_b64 exec, exec, s[4:5]
	s_cbranch_execnz .LBB0_699
	s_or_b64 exec, exec, s[4:5]
